# SwiGLU epilogue: hoist 8 rs[row] loads, counted vmcnt(7) waits, global_ instead of flat_ loads/stores
# speedup vs baseline: 1.0137x; 1.0137x over previous
; #define PG8_STAGE(bufoff, gbase, voff) do { _Pragma("unroll") for (int _i = 0; _i < 2; ++_i) \
;         __builtin_amdgcn_global_load_lds((const unsigned*)((const char*)(gbase) + (voff)[_i]), (PG8_LAS unsigned*)(lds + (bufoff) + ldsw + _i * 8192), 16, 0, 0); } while (0)
; #define PG8_LDA(dst, b, h) do { _Pragma("unroll") for (int m = 0; m < 4; ++m) _Pragma("unroll") for (int k = 0; k < 2; ++k) dst[m][k] = *(const PG8_LAS bf16x8*)(lds + PG8_SA(b, h) + aoff + m * 2048 + k * 1024); } while (0)
; #define PG8_LDB(dst, b, h) do { _Pragma("unroll") for (int n = 0; n < 2; ++n) _Pragma("unroll") for (int k = 0; k < 2; ++k) dst[n][k] = *(const PG8_LAS bf16x8*)(lds + PG8_SB(b, h) + boff + n * 2048 + k * 1024); } while (0)
; #define PG8_MMA(ai, bj, At, Bt) do { __builtin_amdgcn_s_setprio(1); _Pragma("unroll") for (int m = 0; m < 4; ++m) _Pragma("unroll") for (int n = 0; n < 2; ++n) _Pragma("unroll") for (int k = 0; k < 2; ++k) \
;         acc[ai][bj][m][n] = __builtin_amdgcn_mfma_f32_16x16x32_bf16(Bt[n][k], At[m][k], acc[ai][bj][m][n], 0, 0, 0); __builtin_amdgcn_s_setprio(0); } while (0)
; #define PG8_WAIT_V(n) asm volatile("s_waitcnt vmcnt(" #n ")" ::: "memory")
; #define PG8_WAIT_L(n) asm volatile("s_waitcnt lgkmcnt(" #n ")" ::: "memory")
; #define PG8_BAR __builtin_amdgcn_s_barrier()
; #define PG8_SCHED __builtin_amdgcn_sched_barrier(0)
; template <class Epi, class Sched, bool ALIGN_EPI = false, bool SP2 = false>
; __device__ __forceinline__ void gemm_phase(PG8_LAS unsigned char* lds, const Gemm g, const Sched& S, const Epi& E) {
;     ...
;             PG8_LDB(B0, 0, 0); PG8_LDB(B1, 0, 1); PG8_SCHED; PG8_LDA(At, 0, 0); PG8_STAGE(PG8_SA(1, 1), a1 + hstep, voffA);
;             PG8_WAIT_V(8); PG8_WAIT_L(0); PG8_BAR; PG8_MMA(0, 0, At, B0); PG8_MMA(0, 1, At, B1); PG8_BAR; PG8_SCHED;
;             PG8_LDA(At, 0, 1); PG8_STAGE(PG8_SB(0, 0), b2, voffB); PG8_STAGE(PG8_SB(0, 1), b2 + hstep, voffB); PG8_STAGE(PG8_SA(0, 0), a2, voffA);
;             PG8_WAIT_V(8); PG8_WAIT_L(0); PG8_BAR; PG8_MMA(1, 0, At, B0); PG8_MMA(1, 1, At, B1); PG8_BAR; PG8_SCHED;
.LBB0_287:
	s_add_u32 s36, s38, 0xfffc0080
	s_addc_u32 s37, s39, -1
	s_add_i32 s86, 0, 0x10000
	s_cmp_eq_u32 s85, 12
	s_cselect_b32 s59, s19, s37
	s_cselect_b32 s58, s83, s36
	v_add_u32_e32 v134, s86, v151
	s_cselect_b32 s37, s17, s84
	s_cselect_b32 s36, vcc_lo, vcc_hi
	s_add_i32 s88, 0, 0x14000
	ds_read_b128 v[144:147], v134
	ds_read_b128 v[154:157], v134 offset:1024
	ds_read_b128 v[202:205], v134 offset:2048
	ds_read_b128 v[206:209], v134 offset:3072
	v_add_u32_e32 v134, s88, v151
	ds_read_b128 v[210:213], v134
	ds_read_b128 v[214:217], v134 offset:1024
	ds_read_b128 v[218:221], v134 offset:2048
	ds_read_b128 v[222:225], v134 offset:3072
	v_lshl_add_u64 v[134:135], s[38:39], 0, v[142:143]
	s_add_i32 m0, s74, 0xc000
	ds_read_b128 v[226:229], v153
	ds_read_b128 v[230:233], v153 offset:1024
	ds_read_b128 v[234:237], v153 offset:2048
	ds_read_b128 v[238:241], v153 offset:3072
	ds_read_b128 v[242:245], v153 offset:4096
	ds_read_b128 v[246:249], v153 offset:5120
	ds_read_b128 v[176:179], v153 offset:6144
	ds_read_b128 v[194:197], v153 offset:7168
	global_load_lds_dwordx4 v[134:135], off
	v_lshl_add_u64 v[134:135], s[38:39], 0, v[140:141]
	s_add_i32 m0, s74, 0xe000
	s_nop 0
	global_load_lds_dwordx4 v[134:135], off
	s_waitcnt vmcnt(8)
	s_waitcnt lgkmcnt(0)
	s_barrier
	s_setprio 1
	s_waitcnt lgkmcnt(0)
	v_mfma_f32_16x16x32_bf16 v[126:129], v[144:147], v[226:229], v[126:129]
	v_mfma_f32_16x16x32_bf16 v[122:125], v[202:205], v[226:229], v[122:125]
	v_mfma_f32_16x16x32_bf16 v[110:113], v[144:147], v[234:237], v[110:113]
	v_mfma_f32_16x16x32_bf16 v[106:109], v[202:205], v[234:237], v[106:109]
	v_mfma_f32_16x16x32_bf16 v[94:97], v[144:147], v[242:245], v[94:97]
	v_mfma_f32_16x16x32_bf16 v[90:93], v[202:205], v[242:245], v[90:93]
	v_mfma_f32_16x16x32_bf16 v[78:81], v[144:147], v[176:179], v[78:81]
	v_mfma_f32_16x16x32_bf16 v[74:77], v[202:205], v[176:179], v[74:77]
	v_mfma_f32_16x16x32_bf16 v[126:129], v[154:157], v[230:233], v[126:129]
	v_mfma_f32_16x16x32_bf16 v[122:125], v[206:209], v[230:233], v[122:125]
	v_mfma_f32_16x16x32_bf16 v[110:113], v[154:157], v[238:241], v[110:113]
	v_mfma_f32_16x16x32_bf16 v[106:109], v[206:209], v[238:241], v[106:109]
	v_mfma_f32_16x16x32_bf16 v[94:97], v[154:157], v[246:249], v[94:97]
	v_mfma_f32_16x16x32_bf16 v[90:93], v[206:209], v[246:249], v[90:93]
	v_mfma_f32_16x16x32_bf16 v[78:81], v[154:157], v[194:197], v[78:81]
	v_mfma_f32_16x16x32_bf16 v[74:77], v[206:209], v[194:197], v[74:77]
	s_setprio 0
	s_setprio 1
	v_mfma_f32_16x16x32_bf16 v[118:121], v[210:213], v[226:229], v[118:121]
	v_mfma_f32_16x16x32_bf16 v[114:117], v[218:221], v[226:229], v[114:117]
	v_mfma_f32_16x16x32_bf16 v[102:105], v[210:213], v[234:237], v[102:105]
	v_mfma_f32_16x16x32_bf16 v[98:101], v[218:221], v[234:237], v[98:101]
	v_mfma_f32_16x16x32_bf16 v[86:89], v[210:213], v[242:245], v[86:89]
	v_mfma_f32_16x16x32_bf16 v[82:85], v[218:221], v[242:245], v[82:85]
	v_mfma_f32_16x16x32_bf16 v[70:73], v[210:213], v[176:179], v[70:73]
	v_mfma_f32_16x16x32_bf16 v[66:69], v[218:221], v[176:179], v[66:69]
	v_mfma_f32_16x16x32_bf16 v[118:121], v[214:217], v[230:233], v[118:121]
	v_mfma_f32_16x16x32_bf16 v[114:117], v[222:225], v[230:233], v[114:117]
	v_mfma_f32_16x16x32_bf16 v[102:105], v[214:217], v[238:241], v[102:105]
	v_mfma_f32_16x16x32_bf16 v[98:101], v[222:225], v[238:241], v[98:101]
	v_mfma_f32_16x16x32_bf16 v[86:89], v[214:217], v[246:249], v[86:89]
	v_mfma_f32_16x16x32_bf16 v[82:85], v[222:225], v[246:249], v[82:85]
	v_mfma_f32_16x16x32_bf16 v[70:73], v[214:217], v[194:197], v[70:73]
	v_mfma_f32_16x16x32_bf16 v[66:69], v[222:225], v[194:197], v[66:69]
	s_setprio 0
	s_barrier
	s_add_i32 s86, s86, s67
	v_lshl_add_u64 v[134:135], s[36:37], 0, v[16:17]
	s_mov_b32 m0, s86
	ds_read_b128 v[176:179], v153 offset:16384
	ds_read_b128 v[194:197], v153 offset:17408
	ds_read_b128 v[226:229], v153 offset:18432
	ds_read_b128 v[230:233], v153 offset:19456
	ds_read_b128 v[234:237], v153 offset:20480
	ds_read_b128 v[238:241], v153 offset:21504
	ds_read_b128 v[242:245], v153 offset:22528
	ds_read_b128 v[246:249], v153 offset:23552
	global_load_lds_dwordx4 v[134:135], off
	s_add_i32 m0, s86, 0x2000
	s_add_u32 s86, s36, 0x40000
	v_lshl_add_u64 v[136:137], s[36:37], 0, v[130:131]
	s_addc_u32 s87, s37, 0
	s_add_i32 s88, s88, s67
	global_load_lds_dwordx4 v[136:137], off
	v_lshl_add_u64 v[148:149], s[86:87], 0, v[16:17]
	s_mov_b32 m0, s88
	v_lshl_add_u64 v[158:159], s[58:59], 0, v[132:133]
	global_load_lds_dwordx4 v[148:149], off
	v_lshl_add_u64 v[148:149], s[86:87], 0, v[130:131]
	s_add_i32 m0, s88, 0x2000
	s_nop 0
	global_load_lds_dwordx4 v[148:149], off
	v_lshl_add_u64 v[148:149], s[58:59], 0, v[138:139]
	s_mov_b32 m0, s74
	s_nop 0
	global_load_lds_dwordx4 v[148:149], off
	s_mov_b32 m0, s75
	s_nop 0
	global_load_lds_dwordx4 v[158:159], off
	s_waitcnt vmcnt(8)
	s_waitcnt lgkmcnt(0)
	s_barrier
; #define PG8_STAGE(bufoff, gbase, voff) do { _Pragma("unroll") for (int _i = 0; _i < 2; ++_i) \
;         __builtin_amdgcn_global_load_lds((const unsigned*)((const char*)(gbase) + (voff)[_i]), (PG8_LAS unsigned*)(lds + (bufoff) + ldsw + _i * 8192), 16, 0, 0); } while (0)
; #define PG8_LDA(dst, b, h) do { _Pragma("unroll") for (int m = 0; m < 4; ++m) _Pragma("unroll") for (int k = 0; k < 2; ++k) dst[m][k] = *(const PG8_LAS bf16x8*)(lds + PG8_SA(b, h) + aoff + m * 2048 + k * 1024); } while (0)
; #define PG8_LDB(dst, b, h) do { _Pragma("unroll") for (int n = 0; n < 2; ++n) _Pragma("unroll") for (int k = 0; k < 2; ++k) dst[n][k] = *(const PG8_LAS bf16x8*)(lds + PG8_SB(b, h) + boff + n * 2048 + k * 1024); } while (0)
; #define PG8_MMA(ai, bj, At, Bt) do { __builtin_amdgcn_s_setprio(1); _Pragma("unroll") for (int m = 0; m < 4; ++m) _Pragma("unroll") for (int n = 0; n < 2; ++n) _Pragma("unroll") for (int k = 0; k < 2; ++k) \
;         acc[ai][bj][m][n] = __builtin_amdgcn_mfma_f32_16x16x32_bf16(Bt[n][k], At[m][k], acc[ai][bj][m][n], 0, 0, 0); __builtin_amdgcn_s_setprio(0); } while (0)
; #define PG8_WAIT_V(n) asm volatile("s_waitcnt vmcnt(" #n ")" ::: "memory")
; #define PG8_WAIT_L(n) asm volatile("s_waitcnt lgkmcnt(" #n ")" ::: "memory")
; #define PG8_BAR __builtin_amdgcn_s_barrier()
; #define PG8_SCHED __builtin_amdgcn_sched_barrier(0)
; template <class Epi, class Sched, bool ALIGN_EPI = false, bool SP2 = false>
; __device__ __forceinline__ void gemm_phase(PG8_LAS unsigned char* lds, const Gemm g, const Sched& S, const Epi& E) {
;     ...
;             PG8_WAIT_V(8); PG8_WAIT_L(0); PG8_BAR; PG8_MMA(1, 0, At, B0); PG8_MMA(1, 1, At, B1); PG8_BAR; PG8_SCHED;
;             PG8_LDB(B0, 1, 0); PG8_LDB(B1, 1, 1); PG8_SCHED; PG8_LDA(At, 1, 0); PG8_STAGE(PG8_SA(0, 1), a2 + hstep, voffA);
;             PG8_WAIT_V(8); PG8_WAIT_L(0); PG8_BAR; PG8_MMA(0, 0, At, B0); PG8_MMA(0, 1, At, B1); PG8_BAR; PG8_SCHED;
	s_setprio 1
	s_waitcnt lgkmcnt(0)
	v_mfma_f32_16x16x32_bf16 v[62:65], v[144:147], v[176:179], v[62:65]
	v_mfma_f32_16x16x32_bf16 v[58:61], v[202:205], v[176:179], v[58:61]
	v_mfma_f32_16x16x32_bf16 v[46:49], v[144:147], v[226:229], v[46:49]
	v_mfma_f32_16x16x32_bf16 v[42:45], v[202:205], v[226:229], v[42:45]
	v_mfma_f32_16x16x32_bf16 v[30:33], v[144:147], v[234:237], v[30:33]
	v_mfma_f32_16x16x32_bf16 v[26:29], v[202:205], v[234:237], v[26:29]
	v_mfma_f32_16x16x32_bf16 v[12:15], v[144:147], v[242:245], v[12:15]
	v_mfma_f32_16x16x32_bf16 v[8:11], v[202:205], v[242:245], v[8:11]
	v_mfma_f32_16x16x32_bf16 v[62:65], v[154:157], v[194:197], v[62:65]
	v_mfma_f32_16x16x32_bf16 v[58:61], v[206:209], v[194:197], v[58:61]
	v_mfma_f32_16x16x32_bf16 v[46:49], v[154:157], v[230:233], v[46:49]
	v_mfma_f32_16x16x32_bf16 v[42:45], v[206:209], v[230:233], v[42:45]
	v_mfma_f32_16x16x32_bf16 v[30:33], v[154:157], v[238:241], v[30:33]
	v_mfma_f32_16x16x32_bf16 v[26:29], v[206:209], v[238:241], v[26:29]
	v_mfma_f32_16x16x32_bf16 v[12:15], v[154:157], v[246:249], v[12:15]
	v_mfma_f32_16x16x32_bf16 v[8:11], v[206:209], v[246:249], v[8:11]
	s_setprio 0
	s_setprio 1
	v_mfma_f32_16x16x32_bf16 v[54:57], v[210:213], v[176:179], v[54:57]
	v_mfma_f32_16x16x32_bf16 v[50:53], v[218:221], v[176:179], v[50:53]
	v_mfma_f32_16x16x32_bf16 v[38:41], v[210:213], v[226:229], v[38:41]
	v_mfma_f32_16x16x32_bf16 v[34:37], v[218:221], v[226:229], v[34:37]
	v_mfma_f32_16x16x32_bf16 v[22:25], v[210:213], v[234:237], v[22:25]
	v_mfma_f32_16x16x32_bf16 v[18:21], v[218:221], v[234:237], v[18:21]
	v_mfma_f32_16x16x32_bf16 v[4:7], v[210:213], v[242:245], v[4:7]
	v_mfma_f32_16x16x32_bf16 v[0:3], v[218:221], v[242:245], v[0:3]
	v_mfma_f32_16x16x32_bf16 v[54:57], v[214:217], v[194:197], v[54:57]
	v_mfma_f32_16x16x32_bf16 v[50:53], v[222:225], v[194:197], v[50:53]
	v_mfma_f32_16x16x32_bf16 v[38:41], v[214:217], v[230:233], v[38:41]
	v_mfma_f32_16x16x32_bf16 v[34:37], v[222:225], v[230:233], v[34:37]
	v_mfma_f32_16x16x32_bf16 v[22:25], v[214:217], v[238:241], v[22:25]
	v_mfma_f32_16x16x32_bf16 v[18:21], v[222:225], v[238:241], v[18:21]
	v_mfma_f32_16x16x32_bf16 v[4:7], v[214:217], v[246:249], v[4:7]
	v_mfma_f32_16x16x32_bf16 v[0:3], v[222:225], v[246:249], v[0:3]
	s_setprio 0
	s_barrier
	s_add_i32 s86, 0, 0x18000
	v_add_u32_e32 v160, s86, v151
	s_add_i32 s87, 0, 0x1c000
	ds_read_b128 v[144:147], v160
	ds_read_b128 v[154:157], v160 offset:1024
	ds_read_b128 v[176:179], v160 offset:2048
	ds_read_b128 v[194:197], v160 offset:3072
	v_add_u32_e32 v160, s87, v151
	ds_read_b128 v[202:205], v160
	ds_read_b128 v[206:209], v160 offset:1024
	ds_read_b128 v[210:213], v160 offset:2048
	ds_read_b128 v[214:217], v160 offset:3072
	s_add_u32 s58, s58, 0x40000
	s_addc_u32 s59, s59, 0
	s_mov_b32 m0, s76
	v_lshl_add_u64 v[162:163], s[58:59], 0, v[138:139]
	ds_read_b128 v[218:221], v153 offset:32768
	ds_read_b128 v[222:225], v153 offset:33792
	ds_read_b128 v[226:229], v153 offset:34816
	ds_read_b128 v[230:233], v153 offset:35840
	ds_read_b128 v[234:237], v153 offset:36864
	ds_read_b128 v[238:241], v153 offset:37888
	ds_read_b128 v[242:245], v153 offset:38912
	ds_read_b128 v[246:249], v153 offset:39936
	global_load_lds_dwordx4 v[162:163], off
	v_lshl_add_u64 v[162:163], s[58:59], 0, v[132:133]
	s_mov_b32 m0, s77
	s_nop 0
	global_load_lds_dwordx4 v[162:163], off
	s_waitcnt vmcnt(8)
	s_waitcnt lgkmcnt(0)
	s_barrier
	s_setprio 1
	s_waitcnt lgkmcnt(0)
	v_mfma_f32_16x16x32_bf16 v[126:129], v[144:147], v[218:221], v[126:129]
	v_mfma_f32_16x16x32_bf16 v[122:125], v[176:179], v[218:221], v[122:125]
	v_mfma_f32_16x16x32_bf16 v[110:113], v[144:147], v[226:229], v[110:113]
	v_mfma_f32_16x16x32_bf16 v[106:109], v[176:179], v[226:229], v[106:109]
	v_mfma_f32_16x16x32_bf16 v[94:97], v[144:147], v[234:237], v[94:97]
	v_mfma_f32_16x16x32_bf16 v[90:93], v[176:179], v[234:237], v[90:93]
	v_mfma_f32_16x16x32_bf16 v[78:81], v[144:147], v[242:245], v[78:81]
	v_mfma_f32_16x16x32_bf16 v[74:77], v[176:179], v[242:245], v[74:77]
	v_mfma_f32_16x16x32_bf16 v[126:129], v[154:157], v[222:225], v[126:129]
	v_mfma_f32_16x16x32_bf16 v[122:125], v[194:197], v[222:225], v[122:125]
	v_mfma_f32_16x16x32_bf16 v[110:113], v[154:157], v[230:233], v[110:113]
	v_mfma_f32_16x16x32_bf16 v[106:109], v[194:197], v[230:233], v[106:109]
	v_mfma_f32_16x16x32_bf16 v[94:97], v[154:157], v[238:241], v[94:97]
	v_mfma_f32_16x16x32_bf16 v[90:93], v[194:197], v[238:241], v[90:93]
	v_mfma_f32_16x16x32_bf16 v[78:81], v[154:157], v[246:249], v[78:81]
	v_mfma_f32_16x16x32_bf16 v[74:77], v[194:197], v[246:249], v[74:77]
	s_setprio 0
	s_setprio 1
	v_mfma_f32_16x16x32_bf16 v[118:121], v[202:205], v[218:221], v[118:121]
	v_mfma_f32_16x16x32_bf16 v[114:117], v[210:213], v[218:221], v[114:117]
	v_mfma_f32_16x16x32_bf16 v[102:105], v[202:205], v[226:229], v[102:105]
	v_mfma_f32_16x16x32_bf16 v[98:101], v[210:213], v[226:229], v[98:101]
	v_mfma_f32_16x16x32_bf16 v[86:89], v[202:205], v[234:237], v[86:89]
	v_mfma_f32_16x16x32_bf16 v[82:85], v[210:213], v[234:237], v[82:85]
	v_mfma_f32_16x16x32_bf16 v[70:73], v[202:205], v[242:245], v[70:73]
	v_mfma_f32_16x16x32_bf16 v[66:69], v[210:213], v[242:245], v[66:69]
	v_mfma_f32_16x16x32_bf16 v[118:121], v[206:209], v[222:225], v[118:121]
	v_mfma_f32_16x16x32_bf16 v[114:117], v[214:217], v[222:225], v[114:117]
	v_mfma_f32_16x16x32_bf16 v[102:105], v[206:209], v[230:233], v[102:105]
	v_mfma_f32_16x16x32_bf16 v[98:101], v[214:217], v[230:233], v[98:101]
	v_mfma_f32_16x16x32_bf16 v[86:89], v[206:209], v[238:241], v[86:89]
	v_mfma_f32_16x16x32_bf16 v[82:85], v[214:217], v[238:241], v[82:85]
	v_mfma_f32_16x16x32_bf16 v[70:73], v[206:209], v[246:249], v[70:73]
	v_mfma_f32_16x16x32_bf16 v[66:69], v[214:217], v[246:249], v[66:69]
	s_setprio 0
	s_barrier
; #define PG8_STAGE(bufoff, gbase, voff) do { _Pragma("unroll") for (int _i = 0; _i < 2; ++_i) \
;         __builtin_amdgcn_global_load_lds((const unsigned*)((const char*)(gbase) + (voff)[_i]), (PG8_LAS unsigned*)(lds + (bufoff) + ldsw + _i * 8192), 16, 0, 0); } while (0)
; #define PG8_LDA(dst, b, h) do { _Pragma("unroll") for (int m = 0; m < 4; ++m) _Pragma("unroll") for (int k = 0; k < 2; ++k) dst[m][k] = *(const PG8_LAS bf16x8*)(lds + PG8_SA(b, h) + aoff + m * 2048 + k * 1024); } while (0)
; #define PG8_MMA(ai, bj, At, Bt) do { __builtin_amdgcn_s_setprio(1); _Pragma("unroll") for (int m = 0; m < 4; ++m) _Pragma("unroll") for (int n = 0; n < 2; ++n) _Pragma("unroll") for (int k = 0; k < 2; ++k) \
;         acc[ai][bj][m][n] = __builtin_amdgcn_mfma_f32_16x16x32_bf16(Bt[n][k], At[m][k], acc[ai][bj][m][n], 0, 0, 0); __builtin_amdgcn_s_setprio(0); } while (0)
; #define PG8_WAIT_V(n) asm volatile("s_waitcnt vmcnt(" #n ")" ::: "memory")
; #define PG8_WAIT_L(n) asm volatile("s_waitcnt lgkmcnt(" #n ")" ::: "memory")
; #define PG8_BAR __builtin_amdgcn_s_barrier()
; #define PG8_SCHED __builtin_amdgcn_sched_barrier(0)
;     __device__ __forceinline__ void operator()(const f32x4 (&acc)[2][2][4][2], const Unit& u, int wr, int wc, int fr, int fq) const {
;         const int row0 = u.pm * BM + wr * 64 + fr, col0 = u.pn * HALF + wc * 32 + 8 * fq;
; #pragma unroll
;         for (int ai = 0; ai < 2; ++ai)
; #pragma unroll
;             for (int m = 0; m < 4; ++m) { const int row = row0 + ai * HALF + m * 16; const float s = rs[row];
; template <class Epi, class Sched, bool ALIGN_EPI = false, bool SP2 = false>
; __device__ __forceinline__ void gemm_phase(PG8_LAS unsigned char* lds, const Gemm g, const Sched& S, const Epi& E) {
;     ...
;             PG8_LDA(At, 1, 1); PG8_STAGE(PG8_SB(1, 0), b3, voffB); PG8_STAGE(PG8_SB(1, 1), b3 + hstep, voffB); PG8_STAGE(PG8_SA(1, 0), a3, voffA);
;             PG8_WAIT_V(8); PG8_WAIT_L(0); PG8_BAR; PG8_MMA(1, 0, At, B0); PG8_MMA(1, 1, At, B1); PG8_BAR; PG8_SCHED;
	s_add_i32 s58, s86, s67
	v_lshl_add_u64 v[134:135], v[134:135], 0, s[42:43]
	s_mov_b32 m0, s58
	ds_read_b128 v[218:221], v153 offset:49152
	ds_read_b128 v[222:225], v153 offset:50176
	ds_read_b128 v[226:229], v153 offset:51200
	ds_read_b128 v[230:233], v153 offset:52224
	ds_read_b128 v[234:237], v153 offset:53248
	ds_read_b128 v[238:241], v153 offset:54272
	ds_read_b128 v[242:245], v153 offset:55296
	ds_read_b128 v[246:249], v153 offset:56320
	global_load_lds_dwordx4 v[134:135], off
	s_add_i32 m0, s58, 0x2000
	s_add_u32 s36, s36, 0x40080
	v_lshl_add_u64 v[134:135], v[136:137], 0, s[42:43]
	s_addc_u32 s37, s37, 0
	s_add_i32 s58, s87, s67
	global_load_lds_dwordx4 v[134:135], off
	v_lshl_add_u64 v[134:135], s[36:37], 0, v[16:17]
	s_mov_b32 m0, s58
	s_nop 0
	global_load_lds_dwordx4 v[134:135], off
	v_lshl_add_u64 v[134:135], s[36:37], 0, v[130:131]
	s_add_i32 m0, s58, 0x2000
	s_nop 0
	global_load_lds_dwordx4 v[134:135], off
	v_lshl_add_u64 v[134:135], v[148:149], 0, s[42:43]
	s_mov_b32 m0, s78
	s_nop 0
	global_load_lds_dwordx4 v[134:135], off
	v_lshl_add_u64 v[134:135], v[158:159], 0, s[42:43]
	s_mov_b32 m0, s79
	s_nop 0
	global_load_lds_dwordx4 v[134:135], off
	s_waitcnt vmcnt(8)
	s_waitcnt lgkmcnt(0)
	s_barrier
	s_setprio 1
	s_waitcnt lgkmcnt(0)
	v_mfma_f32_16x16x32_bf16 v[62:65], v[144:147], v[218:221], v[62:65]
	v_mfma_f32_16x16x32_bf16 v[58:61], v[176:179], v[218:221], v[58:61]
	v_mfma_f32_16x16x32_bf16 v[46:49], v[144:147], v[226:229], v[46:49]
	v_mfma_f32_16x16x32_bf16 v[42:45], v[176:179], v[226:229], v[42:45]
	v_mfma_f32_16x16x32_bf16 v[30:33], v[144:147], v[234:237], v[30:33]
	v_mfma_f32_16x16x32_bf16 v[26:29], v[176:179], v[234:237], v[26:29]
	v_mfma_f32_16x16x32_bf16 v[12:15], v[144:147], v[242:245], v[12:15]
	v_mfma_f32_16x16x32_bf16 v[8:11], v[176:179], v[242:245], v[8:11]
	v_mfma_f32_16x16x32_bf16 v[62:65], v[154:157], v[222:225], v[62:65]
	v_mfma_f32_16x16x32_bf16 v[58:61], v[194:197], v[222:225], v[58:61]
	v_mfma_f32_16x16x32_bf16 v[46:49], v[154:157], v[230:233], v[46:49]
	v_mfma_f32_16x16x32_bf16 v[42:45], v[194:197], v[230:233], v[42:45]
	v_mfma_f32_16x16x32_bf16 v[30:33], v[154:157], v[238:241], v[30:33]
	v_mfma_f32_16x16x32_bf16 v[26:29], v[194:197], v[238:241], v[26:29]
	v_mfma_f32_16x16x32_bf16 v[12:15], v[154:157], v[246:249], v[12:15]
	v_mfma_f32_16x16x32_bf16 v[8:11], v[194:197], v[246:249], v[8:11]
	s_setprio 0
	s_setprio 1
	v_mfma_f32_16x16x32_bf16 v[54:57], v[202:205], v[218:221], v[54:57]
	v_mfma_f32_16x16x32_bf16 v[50:53], v[210:213], v[218:221], v[50:53]
	v_mfma_f32_16x16x32_bf16 v[38:41], v[202:205], v[226:229], v[38:41]
	v_mfma_f32_16x16x32_bf16 v[34:37], v[210:213], v[226:229], v[34:37]
	v_mfma_f32_16x16x32_bf16 v[22:25], v[202:205], v[234:237], v[22:25]
	v_mfma_f32_16x16x32_bf16 v[18:21], v[210:213], v[234:237], v[18:21]
	v_mfma_f32_16x16x32_bf16 v[4:7], v[202:205], v[242:245], v[4:7]
	v_mfma_f32_16x16x32_bf16 v[0:3], v[210:213], v[242:245], v[0:3]
	v_mfma_f32_16x16x32_bf16 v[54:57], v[206:209], v[222:225], v[54:57]
	v_mfma_f32_16x16x32_bf16 v[50:53], v[214:217], v[222:225], v[50:53]
	v_mfma_f32_16x16x32_bf16 v[38:41], v[206:209], v[230:233], v[38:41]
	v_mfma_f32_16x16x32_bf16 v[34:37], v[214:217], v[230:233], v[34:37]
	v_mfma_f32_16x16x32_bf16 v[22:25], v[206:209], v[238:241], v[22:25]
	v_mfma_f32_16x16x32_bf16 v[18:21], v[214:217], v[238:241], v[18:21]
	v_mfma_f32_16x16x32_bf16 v[4:7], v[206:209], v[246:249], v[4:7]
	v_mfma_f32_16x16x32_bf16 v[0:3], v[214:217], v[246:249], v[0:3]
	s_setprio 0
	s_barrier
	s_add_i32 s85, s85, 2
	s_add_u32 vcc_hi, vcc_hi, 0x100
	s_addc_u32 s84, s84, 0
	s_add_u32 s38, s38, 0x100
	s_addc_u32 s39, s39, 0
	s_cmp_gt_u32 s85, 13
	s_cbranch_scc0 .LBB0_287
	v_lshl_add_u32 v144, s82, 8, v150
	v_ashrrev_i32_e32 v145, 31, v144
	v_lshl_add_u64 v[146:147], v[144:145], 2, s[12:13]
	global_load_dword v202, v[146:147], off
	global_load_dword v204, v[146:147], off offset:64
	global_load_dword v206, v[146:147], off offset:128
	global_load_dword v208, v[146:147], off offset:192
	global_load_dword v210, v[146:147], off offset:512
	global_load_dword v212, v[146:147], off offset:576
	global_load_dword v214, v[146:147], off offset:640
	global_load_dword v216, v[146:147], off offset:704
	s_and_b64 vcc, exec, s[14:15]
	s_cbranch_vccz .LBB0_290
	s_barrier
; __device__ __forceinline__ unsigned cvt_pk_bf16(float lo, float hi) { unsigned r; asm volatile("v_cvt_pk_bf16_f32 %0, %1, %2" : "=v"(r) : "v"(lo), "v"(hi)); return r; }
; __device__ __forceinline__ float silu_f(float x) { return x * __builtin_amdgcn_rcpf(1.0f + __expf(-x)); }
;     __device__ __forceinline__ void operator()(const f32x4 (&acc)[2][2][4][2], const Unit& u, int wr, int wc, int fr, int fq) const {
;     ...
;             for (int m = 0; m < 4; ++m) { const int row = row0 + ai * HALF + m * 16; const float s = rs[row];
;                 const f32x4 g0 = acc[ai][0][m][0] * s, g1 = acc[ai][0][m][1] * s, u0 = acc[ai][1][m][0] * s, u1 = acc[ai][1][m][1] * s;
;                 u32x4 w;
;                 w.x = cvt_pk_bf16(silu_f(g0[0]) * u0[0], silu_f(g0[1]) * u0[1]); w.y = cvt_pk_bf16(silu_f(g0[2]) * u0[2], silu_f(g0[3]) * u0[3]);
;                 w.z = cvt_pk_bf16(silu_f(g1[0]) * u1[0], silu_f(g1[1]) * u1[1]); w.w = cvt_pk_bf16(silu_f(g1[2]) * u1[2], silu_f(g1[3]) * u1[3]);
;                 *(u32x4*)(O + (size_t)row * 2816 + col0) = w; }
.LBB0_290:
	v_lshl_or_b32 v148, s81, 7, v152
	v_ashrrev_i32_e32 v149, 31, v148
	s_mov_b64 s[38:39], -1
	s_andn2_b64 vcc, exec, s[8:9]
	s_waitcnt vmcnt(7)
	v_pk_mul_f32 v[126:127], v[126:127], v[202:203] op_sel_hi:[1,0]
	v_pk_mul_f32 v[136:137], v[116:117], v[202:203] op_sel_hi:[1,0]
	v_pk_mul_f32 v[116:117], v[114:115], v[202:203] op_sel_hi:[1,0]
	v_mul_f32_e32 v114, 0xbfb8aa3b, v126
	v_mul_f32_e32 v115, 0xbfb8aa3b, v127
	v_exp_f32_e32 v114, v114
	v_exp_f32_e32 v115, v115
	v_pk_mul_f32 v[118:119], v[118:119], v[202:203] op_sel_hi:[1,0]
	v_pk_mul_f32 v[128:129], v[128:129], v[202:203] op_sel_hi:[1,0]
	v_add_f32_e32 v114, 1.0, v114
	v_add_f32_e32 v115, 1.0, v115
	v_rcp_f32_e32 v114, v114
	v_rcp_f32_e32 v115, v115
	v_pk_mul_f32 v[120:121], v[120:121], v[202:203] op_sel_hi:[1,0]
	v_pk_mul_f32 v[122:123], v[122:123], v[202:203] op_sel_hi:[1,0]
	v_mul_f32_e32 v114, v126, v114
	v_mul_f32_e32 v115, v127, v115
	v_mul_f32_e32 v114, v118, v114
	v_mul_f32_e32 v115, v119, v115
	v_cvt_pk_bf16_f32 v114, v114, v115
	v_mul_f32_e32 v115, 0xbfb8aa3b, v128
	v_mul_f32_e32 v118, 0xbfb8aa3b, v129
	v_exp_f32_e32 v115, v115
	v_exp_f32_e32 v118, v118
	v_pk_mul_f32 v[124:125], v[124:125], v[202:203] op_sel_hi:[1,0]
	v_add_f32_e32 v115, 1.0, v115
	v_add_f32_e32 v118, 1.0, v118
	v_rcp_f32_e32 v115, v115
	v_rcp_f32_e32 v118, v118
	v_mul_f32_e32 v115, v128, v115
	v_mul_f32_e32 v118, v129, v118
	v_mul_f32_e32 v115, v120, v115
	v_mul_f32_e32 v118, v121, v118
	v_cvt_pk_bf16_f32 v115, v115, v118
	v_mul_f32_e32 v118, 0xbfb8aa3b, v122
	v_exp_f32_e32 v118, v118
	v_lshlrev_b64 v[120:121], 1, v[148:149]
	v_add_f32_e32 v118, 1.0, v118
	v_rcp_f32_e32 v118, v118
	s_nop 0
	v_mul_f32_e32 v118, v122, v118
	v_mul_f32_e32 v116, v116, v118
	v_mul_f32_e32 v118, 0xbfb8aa3b, v123
	v_exp_f32_e32 v118, v118
	s_nop 0
	v_add_f32_e32 v118, 1.0, v118
	v_rcp_f32_e32 v118, v118
	s_nop 0
	v_mul_f32_e32 v118, v123, v118
	v_mul_f32_e32 v117, v117, v118
	v_cvt_pk_bf16_f32 v116, v116, v117
	v_mul_f32_e32 v117, 0xbfb8aa3b, v124
	v_mul_f32_e32 v118, 0xbfb8aa3b, v125
	v_exp_f32_e32 v117, v117
	v_exp_f32_e32 v118, v118
	v_add_f32_e32 v117, 1.0, v117
	v_add_f32_e32 v118, 1.0, v118
	v_rcp_f32_e32 v117, v117
	v_rcp_f32_e32 v118, v118
	v_mul_f32_e32 v117, v124, v117
	v_mul_f32_e32 v118, v125, v118
	v_mul_f32_e32 v117, v136, v117
	v_mul_f32_e32 v118, v137, v118
	v_cvt_pk_bf16_f32 v117, v117, v118
	v_mov_b64_e32 v[118:119], s[10:11]
	v_mad_i64_i32 v[122:123], s[36:37], v144, s31, v[118:119]
	v_lshl_add_u64 v[122:123], v[122:123], 0, v[120:121]
	global_store_dwordx4 v[122:123], v[114:117], off
	s_nop 1
	v_or_b32_e32 v114, 16, v144
	s_waitcnt vmcnt(7)
	v_pk_mul_f32 v[110:111], v[110:111], v[204:205] op_sel_hi:[1,0]
	v_pk_mul_f32 v[122:123], v[100:101], v[204:205] op_sel_hi:[1,0]
	v_pk_mul_f32 v[100:101], v[98:99], v[204:205] op_sel_hi:[1,0]
	v_mul_f32_e32 v98, 0xbfb8aa3b, v110
	v_mul_f32_e32 v99, 0xbfb8aa3b, v111
	v_exp_f32_e32 v98, v98
	v_exp_f32_e32 v99, v99
	v_pk_mul_f32 v[102:103], v[102:103], v[204:205] op_sel_hi:[1,0]
	v_pk_mul_f32 v[112:113], v[112:113], v[204:205] op_sel_hi:[1,0]
	v_add_f32_e32 v98, 1.0, v98
	v_add_f32_e32 v99, 1.0, v99
	v_rcp_f32_e32 v98, v98
	v_rcp_f32_e32 v99, v99
	v_pk_mul_f32 v[104:105], v[104:105], v[204:205] op_sel_hi:[1,0]
	v_pk_mul_f32 v[106:107], v[106:107], v[204:205] op_sel_hi:[1,0]
	v_mul_f32_e32 v98, v110, v98
	v_mul_f32_e32 v99, v111, v99
	v_mul_f32_e32 v98, v102, v98
	v_mul_f32_e32 v99, v103, v99
	v_cvt_pk_bf16_f32 v98, v98, v99
	v_mul_f32_e32 v99, 0xbfb8aa3b, v112
	v_mul_f32_e32 v102, 0xbfb8aa3b, v113
	v_exp_f32_e32 v99, v99
	v_exp_f32_e32 v102, v102
	v_pk_mul_f32 v[108:109], v[108:109], v[204:205] op_sel_hi:[1,0]
	v_add_f32_e32 v99, 1.0, v99
	v_add_f32_e32 v102, 1.0, v102
	v_rcp_f32_e32 v99, v99
	v_rcp_f32_e32 v102, v102
	v_mul_f32_e32 v99, v112, v99
	v_mul_f32_e32 v102, v113, v102
	v_mul_f32_e32 v99, v104, v99
	v_mul_f32_e32 v102, v105, v102
	v_cvt_pk_bf16_f32 v99, v99, v102
	v_mul_f32_e32 v102, 0xbfb8aa3b, v106
	v_exp_f32_e32 v102, v102
	s_nop 0
	v_add_f32_e32 v102, 1.0, v102
	v_rcp_f32_e32 v102, v102
	s_nop 0
	v_mul_f32_e32 v102, v106, v102
	v_mul_f32_e32 v100, v100, v102
	v_mul_f32_e32 v102, 0xbfb8aa3b, v107
	v_exp_f32_e32 v102, v102
	s_nop 0
	v_add_f32_e32 v102, 1.0, v102
	v_rcp_f32_e32 v102, v102
	s_nop 0
	v_mul_f32_e32 v102, v107, v102
	v_mul_f32_e32 v101, v101, v102
	v_cvt_pk_bf16_f32 v100, v100, v101
	v_mul_f32_e32 v101, 0xbfb8aa3b, v108
	v_mul_f32_e32 v102, 0xbfb8aa3b, v109
	v_exp_f32_e32 v101, v101
	v_exp_f32_e32 v102, v102
	v_add_f32_e32 v101, 1.0, v101
	v_add_f32_e32 v102, 1.0, v102
	v_rcp_f32_e32 v101, v101
	v_rcp_f32_e32 v102, v102
	v_mul_f32_e32 v101, v108, v101
	v_mul_f32_e32 v102, v109, v102
	v_mul_f32_e32 v101, v122, v101
	v_mul_f32_e32 v102, v123, v102
	v_cvt_pk_bf16_f32 v101, v101, v102
	v_mad_i64_i32 v[102:103], s[36:37], v114, s31, v[118:119]
	v_lshl_add_u64 v[102:103], v[102:103], 0, v[120:121]
	global_store_dwordx4 v[102:103], v[98:101], off
	s_nop 1
	v_or_b32_e32 v98, 32, v144
	s_waitcnt vmcnt(7)
; __device__ __forceinline__ unsigned cvt_pk_bf16(float lo, float hi) { unsigned r; asm volatile("v_cvt_pk_bf16_f32 %0, %1, %2" : "=v"(r) : "v"(lo), "v"(hi)); return r; }
; __device__ __forceinline__ float silu_f(float x) { return x * __builtin_amdgcn_rcpf(1.0f + __expf(-x)); }
;     __device__ __forceinline__ void operator()(const f32x4 (&acc)[2][2][4][2], const Unit& u, int wr, int wc, int fr, int fq) const {
;     ...
;             for (int m = 0; m < 4; ++m) { const int row = row0 + ai * HALF + m * 16; const float s = rs[row];
;                 const f32x4 g0 = acc[ai][0][m][0] * s, g1 = acc[ai][0][m][1] * s, u0 = acc[ai][1][m][0] * s, u1 = acc[ai][1][m][1] * s;
;                 u32x4 w;
;                 w.x = cvt_pk_bf16(silu_f(g0[0]) * u0[0], silu_f(g0[1]) * u0[1]); w.y = cvt_pk_bf16(silu_f(g0[2]) * u0[2], silu_f(g0[3]) * u0[3]);
;                 w.z = cvt_pk_bf16(silu_f(g1[0]) * u1[0], silu_f(g1[1]) * u1[1]); w.w = cvt_pk_bf16(silu_f(g1[2]) * u1[2], silu_f(g1[3]) * u1[3]);
;                 *(u32x4*)(O + (size_t)row * 2816 + col0) = w; }
	v_pk_mul_f32 v[94:95], v[94:95], v[206:207] op_sel_hi:[1,0]
	v_pk_mul_f32 v[102:103], v[84:85], v[206:207] op_sel_hi:[1,0]
	v_pk_mul_f32 v[84:85], v[82:83], v[206:207] op_sel_hi:[1,0]
	v_mul_f32_e32 v82, 0xbfb8aa3b, v94
	v_mul_f32_e32 v83, 0xbfb8aa3b, v95
	v_exp_f32_e32 v82, v82
	v_exp_f32_e32 v83, v83
	v_pk_mul_f32 v[86:87], v[86:87], v[206:207] op_sel_hi:[1,0]
	v_pk_mul_f32 v[96:97], v[96:97], v[206:207] op_sel_hi:[1,0]
	v_add_f32_e32 v82, 1.0, v82
	v_add_f32_e32 v83, 1.0, v83
	v_rcp_f32_e32 v82, v82
	v_rcp_f32_e32 v83, v83
	v_pk_mul_f32 v[88:89], v[88:89], v[206:207] op_sel_hi:[1,0]
	v_pk_mul_f32 v[90:91], v[90:91], v[206:207] op_sel_hi:[1,0]
	v_mul_f32_e32 v82, v94, v82
	v_mul_f32_e32 v83, v95, v83
	v_mul_f32_e32 v82, v86, v82
	v_mul_f32_e32 v83, v87, v83
	v_cvt_pk_bf16_f32 v82, v82, v83
	v_mul_f32_e32 v83, 0xbfb8aa3b, v96
	v_mul_f32_e32 v86, 0xbfb8aa3b, v97
	v_exp_f32_e32 v83, v83
	v_exp_f32_e32 v86, v86
	v_pk_mul_f32 v[92:93], v[92:93], v[206:207] op_sel_hi:[1,0]
	v_add_f32_e32 v83, 1.0, v83
	v_add_f32_e32 v86, 1.0, v86
	v_rcp_f32_e32 v83, v83
	v_rcp_f32_e32 v86, v86
	v_mul_f32_e32 v83, v96, v83
	v_mul_f32_e32 v86, v97, v86
	v_mul_f32_e32 v83, v88, v83
	v_mul_f32_e32 v86, v89, v86
	v_cvt_pk_bf16_f32 v83, v83, v86
	v_mul_f32_e32 v86, 0xbfb8aa3b, v90
	v_exp_f32_e32 v86, v86
	s_nop 0
	v_add_f32_e32 v86, 1.0, v86
	v_rcp_f32_e32 v86, v86
	s_nop 0
	v_mul_f32_e32 v86, v90, v86
	v_mul_f32_e32 v84, v84, v86
	v_mul_f32_e32 v86, 0xbfb8aa3b, v91
	v_exp_f32_e32 v86, v86
	s_nop 0
	v_add_f32_e32 v86, 1.0, v86
	v_rcp_f32_e32 v86, v86
	s_nop 0
	v_mul_f32_e32 v86, v91, v86
	v_mul_f32_e32 v85, v85, v86
	v_cvt_pk_bf16_f32 v84, v84, v85
	v_mul_f32_e32 v85, 0xbfb8aa3b, v92
	v_mul_f32_e32 v86, 0xbfb8aa3b, v93
	v_exp_f32_e32 v85, v85
	v_exp_f32_e32 v86, v86
	v_add_f32_e32 v85, 1.0, v85
	v_add_f32_e32 v86, 1.0, v86
	v_rcp_f32_e32 v85, v85
	v_rcp_f32_e32 v86, v86
	v_mul_f32_e32 v85, v92, v85
	v_mul_f32_e32 v86, v93, v86
	v_mul_f32_e32 v85, v102, v85
	v_mul_f32_e32 v86, v103, v86
	v_cvt_pk_bf16_f32 v85, v85, v86
	v_mad_i64_i32 v[86:87], s[36:37], v98, s31, v[118:119]
	v_lshl_add_u64 v[86:87], v[86:87], 0, v[120:121]
	global_store_dwordx4 v[86:87], v[82:85], off
	s_nop 1
	v_or_b32_e32 v82, 48, v144
	s_waitcnt vmcnt(7)
	v_pk_mul_f32 v[78:79], v[78:79], v[208:209] op_sel_hi:[1,0]
	v_pk_mul_f32 v[86:87], v[68:69], v[208:209] op_sel_hi:[1,0]
	v_pk_mul_f32 v[68:69], v[66:67], v[208:209] op_sel_hi:[1,0]
	v_mul_f32_e32 v66, 0xbfb8aa3b, v78
	v_mul_f32_e32 v67, 0xbfb8aa3b, v79
	v_exp_f32_e32 v66, v66
	v_exp_f32_e32 v67, v67
	v_pk_mul_f32 v[70:71], v[70:71], v[208:209] op_sel_hi:[1,0]
	v_pk_mul_f32 v[80:81], v[80:81], v[208:209] op_sel_hi:[1,0]
	v_add_f32_e32 v66, 1.0, v66
	v_add_f32_e32 v67, 1.0, v67
	v_rcp_f32_e32 v66, v66
	v_rcp_f32_e32 v67, v67
	v_pk_mul_f32 v[72:73], v[72:73], v[208:209] op_sel_hi:[1,0]
	v_pk_mul_f32 v[74:75], v[74:75], v[208:209] op_sel_hi:[1,0]
	v_mul_f32_e32 v66, v78, v66
	v_mul_f32_e32 v67, v79, v67
	v_mul_f32_e32 v66, v70, v66
	v_mul_f32_e32 v67, v71, v67
	v_cvt_pk_bf16_f32 v66, v66, v67
	v_mul_f32_e32 v67, 0xbfb8aa3b, v80
	v_mul_f32_e32 v70, 0xbfb8aa3b, v81
	v_exp_f32_e32 v67, v67
	v_exp_f32_e32 v70, v70
	v_pk_mul_f32 v[76:77], v[76:77], v[208:209] op_sel_hi:[1,0]
	v_add_f32_e32 v67, 1.0, v67
	v_add_f32_e32 v70, 1.0, v70
	v_rcp_f32_e32 v67, v67
	v_rcp_f32_e32 v70, v70
	v_mul_f32_e32 v67, v80, v67
	v_mul_f32_e32 v70, v81, v70
	v_mul_f32_e32 v67, v72, v67
	v_mul_f32_e32 v70, v73, v70
	v_cvt_pk_bf16_f32 v67, v67, v70
	v_mul_f32_e32 v70, 0xbfb8aa3b, v74
	v_exp_f32_e32 v70, v70
	s_nop 0
	v_add_f32_e32 v70, 1.0, v70
	v_rcp_f32_e32 v70, v70
	s_nop 0
	v_mul_f32_e32 v70, v74, v70
	v_mul_f32_e32 v68, v68, v70
	v_mul_f32_e32 v70, 0xbfb8aa3b, v75
	v_exp_f32_e32 v70, v70
	s_nop 0
	v_add_f32_e32 v70, 1.0, v70
	v_rcp_f32_e32 v70, v70
	s_nop 0
	v_mul_f32_e32 v70, v75, v70
	v_mul_f32_e32 v69, v69, v70
	v_cvt_pk_bf16_f32 v68, v68, v69
	v_mul_f32_e32 v69, 0xbfb8aa3b, v76
	v_mul_f32_e32 v70, 0xbfb8aa3b, v77
	v_exp_f32_e32 v69, v69
	v_exp_f32_e32 v70, v70
	v_add_f32_e32 v69, 1.0, v69
	v_add_f32_e32 v70, 1.0, v70
	v_rcp_f32_e32 v69, v69
	v_rcp_f32_e32 v70, v70
	v_mul_f32_e32 v69, v76, v69
	v_mul_f32_e32 v70, v77, v70
	v_mul_f32_e32 v69, v86, v69
	v_mul_f32_e32 v70, v87, v70
	v_cvt_pk_bf16_f32 v69, v69, v70
	v_mad_i64_i32 v[70:71], s[36:37], v82, s31, v[118:119]
	v_lshl_add_u64 v[70:71], v[70:71], 0, v[120:121]
	global_store_dwordx4 v[70:71], v[66:69], off
	s_nop 1
	v_add_u32_e32 v67, 0x80, v144
	s_waitcnt vmcnt(7)
	v_pk_mul_f32 v[62:63], v[62:63], v[210:211] op_sel_hi:[1,0]
	v_pk_mul_f32 v[68:69], v[52:53], v[210:211] op_sel_hi:[1,0]
	v_pk_mul_f32 v[52:53], v[50:51], v[210:211] op_sel_hi:[1,0]
	v_mul_f32_e32 v50, 0xbfb8aa3b, v62
	v_mul_f32_e32 v51, 0xbfb8aa3b, v63
	v_exp_f32_e32 v50, v50
	v_exp_f32_e32 v51, v51
	v_pk_mul_f32 v[54:55], v[54:55], v[210:211] op_sel_hi:[1,0]
	v_pk_mul_f32 v[64:65], v[64:65], v[210:211] op_sel_hi:[1,0]
	v_add_f32_e32 v50, 1.0, v50
	v_add_f32_e32 v51, 1.0, v51
	v_rcp_f32_e32 v50, v50
	v_rcp_f32_e32 v51, v51
	v_pk_mul_f32 v[56:57], v[56:57], v[210:211] op_sel_hi:[1,0]
	v_pk_mul_f32 v[58:59], v[58:59], v[210:211] op_sel_hi:[1,0]
	v_mul_f32_e32 v50, v62, v50
	v_mul_f32_e32 v51, v63, v51
	v_mul_f32_e32 v50, v54, v50
	v_mul_f32_e32 v51, v55, v51
	v_cvt_pk_bf16_f32 v50, v50, v51
	v_mul_f32_e32 v51, 0xbfb8aa3b, v64
	v_mul_f32_e32 v54, 0xbfb8aa3b, v65
	v_exp_f32_e32 v51, v51
	v_exp_f32_e32 v54, v54
	v_pk_mul_f32 v[60:61], v[60:61], v[210:211] op_sel_hi:[1,0]
	v_add_f32_e32 v51, 1.0, v51
	v_add_f32_e32 v54, 1.0, v54
	v_rcp_f32_e32 v51, v51
	v_rcp_f32_e32 v54, v54
	v_mul_f32_e32 v51, v64, v51
	v_mul_f32_e32 v54, v65, v54
	v_mul_f32_e32 v51, v56, v51
	v_mul_f32_e32 v54, v57, v54
	v_cvt_pk_bf16_f32 v51, v51, v54
	v_mul_f32_e32 v54, 0xbfb8aa3b, v58
	v_exp_f32_e32 v54, v54
	s_nop 0
	v_add_f32_e32 v54, 1.0, v54
	v_rcp_f32_e32 v54, v54
	s_nop 0
	v_mul_f32_e32 v54, v58, v54
	v_mul_f32_e32 v52, v52, v54
	v_mul_f32_e32 v54, 0xbfb8aa3b, v59
	v_exp_f32_e32 v54, v54
	s_nop 0
	v_add_f32_e32 v54, 1.0, v54
	v_rcp_f32_e32 v54, v54
	s_nop 0
	v_mul_f32_e32 v54, v59, v54
	v_mul_f32_e32 v53, v53, v54
	v_cvt_pk_bf16_f32 v52, v52, v53
	v_mul_f32_e32 v53, 0xbfb8aa3b, v60
	v_mul_f32_e32 v54, 0xbfb8aa3b, v61
	v_exp_f32_e32 v53, v53
	v_exp_f32_e32 v54, v54
	v_add_f32_e32 v53, 1.0, v53
	v_add_f32_e32 v54, 1.0, v54
	v_rcp_f32_e32 v53, v53
	v_rcp_f32_e32 v54, v54
	v_mul_f32_e32 v53, v60, v53
	v_mul_f32_e32 v54, v61, v54
	v_mul_f32_e32 v53, v68, v53
	v_mul_f32_e32 v54, v69, v54
	v_cvt_pk_bf16_f32 v53, v53, v54
	v_mad_i64_i32 v[54:55], s[36:37], v67, s31, v[118:119]
	v_lshl_add_u64 v[54:55], v[54:55], 0, v[120:121]
	global_store_dwordx4 v[54:55], v[50:53], off
	s_nop 1
	v_add_u32_e32 v51, 0x90, v144
	s_waitcnt vmcnt(7)
; __device__ __forceinline__ unsigned cvt_pk_bf16(float lo, float hi) { unsigned r; asm volatile("v_cvt_pk_bf16_f32 %0, %1, %2" : "=v"(r) : "v"(lo), "v"(hi)); return r; }
; __device__ __forceinline__ float silu_f(float x) { return x * __builtin_amdgcn_rcpf(1.0f + __expf(-x)); }
;     __device__ __forceinline__ void operator()(const f32x4 (&acc)[2][2][4][2], const Unit& u, int wr, int wc, int fr, int fq) const {
;     ...
;             for (int m = 0; m < 4; ++m) { const int row = row0 + ai * HALF + m * 16; const float s = rs[row];
;                 const f32x4 g0 = acc[ai][0][m][0] * s, g1 = acc[ai][0][m][1] * s, u0 = acc[ai][1][m][0] * s, u1 = acc[ai][1][m][1] * s;
;                 u32x4 w;
;                 w.x = cvt_pk_bf16(silu_f(g0[0]) * u0[0], silu_f(g0[1]) * u0[1]); w.y = cvt_pk_bf16(silu_f(g0[2]) * u0[2], silu_f(g0[3]) * u0[3]);
;                 w.z = cvt_pk_bf16(silu_f(g1[0]) * u1[0], silu_f(g1[1]) * u1[1]); w.w = cvt_pk_bf16(silu_f(g1[2]) * u1[2], silu_f(g1[3]) * u1[3]);
;                 *(u32x4*)(O + (size_t)row * 2816 + col0) = w; }
	v_pk_mul_f32 v[46:47], v[46:47], v[212:213] op_sel_hi:[1,0]
	v_pk_mul_f32 v[52:53], v[36:37], v[212:213] op_sel_hi:[1,0]
	v_pk_mul_f32 v[36:37], v[34:35], v[212:213] op_sel_hi:[1,0]
	v_mul_f32_e32 v34, 0xbfb8aa3b, v46
	v_mul_f32_e32 v35, 0xbfb8aa3b, v47
	v_exp_f32_e32 v34, v34
	v_exp_f32_e32 v35, v35
	v_pk_mul_f32 v[38:39], v[38:39], v[212:213] op_sel_hi:[1,0]
	v_pk_mul_f32 v[48:49], v[48:49], v[212:213] op_sel_hi:[1,0]
	v_add_f32_e32 v34, 1.0, v34
	v_add_f32_e32 v35, 1.0, v35
	v_rcp_f32_e32 v34, v34
	v_rcp_f32_e32 v35, v35
	v_pk_mul_f32 v[40:41], v[40:41], v[212:213] op_sel_hi:[1,0]
	v_pk_mul_f32 v[42:43], v[42:43], v[212:213] op_sel_hi:[1,0]
	v_mul_f32_e32 v34, v46, v34
	v_mul_f32_e32 v35, v47, v35
	v_mul_f32_e32 v34, v38, v34
	v_mul_f32_e32 v35, v39, v35
	v_cvt_pk_bf16_f32 v34, v34, v35
	v_mul_f32_e32 v35, 0xbfb8aa3b, v48
	v_mul_f32_e32 v38, 0xbfb8aa3b, v49
	v_exp_f32_e32 v35, v35
	v_exp_f32_e32 v38, v38
	v_pk_mul_f32 v[44:45], v[44:45], v[212:213] op_sel_hi:[1,0]
	v_add_f32_e32 v35, 1.0, v35
	v_add_f32_e32 v38, 1.0, v38
	v_rcp_f32_e32 v35, v35
	v_rcp_f32_e32 v38, v38
	v_mul_f32_e32 v35, v48, v35
	v_mul_f32_e32 v38, v49, v38
	v_mul_f32_e32 v35, v40, v35
	v_mul_f32_e32 v38, v41, v38
	v_cvt_pk_bf16_f32 v35, v35, v38
	v_mul_f32_e32 v38, 0xbfb8aa3b, v42
	v_exp_f32_e32 v38, v38
	s_nop 0
	v_add_f32_e32 v38, 1.0, v38
	v_rcp_f32_e32 v38, v38
	s_nop 0
	v_mul_f32_e32 v38, v42, v38
	v_mul_f32_e32 v36, v36, v38
	v_mul_f32_e32 v38, 0xbfb8aa3b, v43
	v_exp_f32_e32 v38, v38
	s_nop 0
	v_add_f32_e32 v38, 1.0, v38
	v_rcp_f32_e32 v38, v38
	s_nop 0
	v_mul_f32_e32 v38, v43, v38
	v_mul_f32_e32 v37, v37, v38
	v_cvt_pk_bf16_f32 v36, v36, v37
	v_mul_f32_e32 v37, 0xbfb8aa3b, v44
	v_mul_f32_e32 v38, 0xbfb8aa3b, v45
	v_exp_f32_e32 v37, v37
	v_exp_f32_e32 v38, v38
	v_add_f32_e32 v37, 1.0, v37
	v_add_f32_e32 v38, 1.0, v38
	v_rcp_f32_e32 v37, v37
	v_rcp_f32_e32 v38, v38
	v_mul_f32_e32 v37, v44, v37
	v_mul_f32_e32 v38, v45, v38
	v_mul_f32_e32 v37, v52, v37
	v_mul_f32_e32 v38, v53, v38
	v_cvt_pk_bf16_f32 v37, v37, v38
	v_mad_i64_i32 v[38:39], s[36:37], v51, s31, v[118:119]
	v_lshl_add_u64 v[38:39], v[38:39], 0, v[120:121]
	global_store_dwordx4 v[38:39], v[34:37], off
	s_nop 1
	v_add_u32_e32 v35, 0xa0, v144
	s_waitcnt vmcnt(7)
	v_pk_mul_f32 v[30:31], v[30:31], v[214:215] op_sel_hi:[1,0]
	v_pk_mul_f32 v[36:37], v[20:21], v[214:215] op_sel_hi:[1,0]
	v_pk_mul_f32 v[20:21], v[18:19], v[214:215] op_sel_hi:[1,0]
	v_mul_f32_e32 v18, 0xbfb8aa3b, v30
	v_mul_f32_e32 v19, 0xbfb8aa3b, v31
	v_exp_f32_e32 v18, v18
	v_exp_f32_e32 v19, v19
	v_pk_mul_f32 v[22:23], v[22:23], v[214:215] op_sel_hi:[1,0]
	v_pk_mul_f32 v[32:33], v[32:33], v[214:215] op_sel_hi:[1,0]
	v_add_f32_e32 v18, 1.0, v18
	v_add_f32_e32 v19, 1.0, v19
	v_rcp_f32_e32 v18, v18
	v_rcp_f32_e32 v19, v19
	v_pk_mul_f32 v[24:25], v[24:25], v[214:215] op_sel_hi:[1,0]
	v_pk_mul_f32 v[26:27], v[26:27], v[214:215] op_sel_hi:[1,0]
	v_mul_f32_e32 v18, v30, v18
	v_mul_f32_e32 v19, v31, v19
	v_mul_f32_e32 v18, v22, v18
	v_mul_f32_e32 v19, v23, v19
	v_cvt_pk_bf16_f32 v18, v18, v19
	v_mul_f32_e32 v19, 0xbfb8aa3b, v32
	v_mul_f32_e32 v22, 0xbfb8aa3b, v33
	v_exp_f32_e32 v19, v19
	v_exp_f32_e32 v22, v22
	v_pk_mul_f32 v[28:29], v[28:29], v[214:215] op_sel_hi:[1,0]
	v_add_f32_e32 v19, 1.0, v19
	v_add_f32_e32 v22, 1.0, v22
	v_rcp_f32_e32 v19, v19
	v_rcp_f32_e32 v22, v22
	v_mul_f32_e32 v19, v32, v19
	v_mul_f32_e32 v22, v33, v22
	v_mul_f32_e32 v19, v24, v19
	v_mul_f32_e32 v22, v25, v22
	v_cvt_pk_bf16_f32 v19, v19, v22
	v_mul_f32_e32 v22, 0xbfb8aa3b, v26
	v_exp_f32_e32 v22, v22
	s_nop 0
	v_add_f32_e32 v22, 1.0, v22
	v_rcp_f32_e32 v22, v22
	s_nop 0
	v_mul_f32_e32 v22, v26, v22
	v_mul_f32_e32 v20, v20, v22
	v_mul_f32_e32 v22, 0xbfb8aa3b, v27
	v_exp_f32_e32 v22, v22
	s_nop 0
	v_add_f32_e32 v22, 1.0, v22
	v_rcp_f32_e32 v22, v22
	s_nop 0
	v_mul_f32_e32 v22, v27, v22
	v_mul_f32_e32 v21, v21, v22
	v_cvt_pk_bf16_f32 v20, v20, v21
	v_mul_f32_e32 v21, 0xbfb8aa3b, v28
	v_mul_f32_e32 v22, 0xbfb8aa3b, v29
	v_exp_f32_e32 v21, v21
	v_exp_f32_e32 v22, v22
	v_add_f32_e32 v21, 1.0, v21
	v_add_f32_e32 v22, 1.0, v22
	v_rcp_f32_e32 v21, v21
	v_rcp_f32_e32 v22, v22
	v_mul_f32_e32 v21, v28, v21
	v_mul_f32_e32 v22, v29, v22
	v_mul_f32_e32 v21, v36, v21
	v_mul_f32_e32 v22, v37, v22
	v_cvt_pk_bf16_f32 v21, v21, v22
	v_mad_i64_i32 v[22:23], s[36:37], v35, s31, v[118:119]
	v_lshl_add_u64 v[22:23], v[22:23], 0, v[120:121]
	global_store_dwordx4 v[22:23], v[18:21], off
	s_nop 1
	v_add_u32_e32 v19, 0xb0, v144
	s_waitcnt vmcnt(7)
	v_pk_mul_f32 v[12:13], v[12:13], v[216:217] op_sel_hi:[1,0]
	v_pk_mul_f32 v[20:21], v[2:3], v[216:217] op_sel_hi:[1,0]
	v_pk_mul_f32 v[2:3], v[0:1], v[216:217] op_sel_hi:[1,0]
	v_mul_f32_e32 v0, 0xbfb8aa3b, v12
	v_mul_f32_e32 v1, 0xbfb8aa3b, v13
	v_exp_f32_e32 v0, v0
	v_exp_f32_e32 v1, v1
	v_pk_mul_f32 v[4:5], v[4:5], v[216:217] op_sel_hi:[1,0]
	v_pk_mul_f32 v[14:15], v[14:15], v[216:217] op_sel_hi:[1,0]
	v_add_f32_e32 v0, 1.0, v0
	v_add_f32_e32 v1, 1.0, v1
	v_rcp_f32_e32 v0, v0
	v_rcp_f32_e32 v1, v1
	v_pk_mul_f32 v[6:7], v[6:7], v[216:217] op_sel_hi:[1,0]
	v_pk_mul_f32 v[8:9], v[8:9], v[216:217] op_sel_hi:[1,0]
	v_mul_f32_e32 v0, v12, v0
	v_mul_f32_e32 v1, v13, v1
	v_mul_f32_e32 v0, v4, v0
	v_mul_f32_e32 v1, v5, v1
	v_cvt_pk_bf16_f32 v0, v0, v1
	v_mul_f32_e32 v1, 0xbfb8aa3b, v14
	v_mul_f32_e32 v4, 0xbfb8aa3b, v15
	v_exp_f32_e32 v1, v1
	v_exp_f32_e32 v4, v4
	v_pk_mul_f32 v[10:11], v[10:11], v[216:217] op_sel_hi:[1,0]
	v_add_f32_e32 v1, 1.0, v1
	v_add_f32_e32 v4, 1.0, v4
	v_rcp_f32_e32 v1, v1
	v_rcp_f32_e32 v4, v4
	v_mul_f32_e32 v1, v14, v1
	v_mul_f32_e32 v4, v15, v4
	v_mul_f32_e32 v1, v6, v1
	v_mul_f32_e32 v4, v7, v4
	v_cvt_pk_bf16_f32 v1, v1, v4
	v_mul_f32_e32 v4, 0xbfb8aa3b, v8
	v_exp_f32_e32 v4, v4
	s_nop 0
	v_add_f32_e32 v4, 1.0, v4
	v_rcp_f32_e32 v4, v4
	s_nop 0
	v_mul_f32_e32 v4, v8, v4
	v_mul_f32_e32 v2, v2, v4
	v_mul_f32_e32 v4, 0xbfb8aa3b, v9
	v_exp_f32_e32 v4, v4
	s_nop 0
	v_add_f32_e32 v4, 1.0, v4
	v_rcp_f32_e32 v4, v4
	s_nop 0
	v_mul_f32_e32 v4, v9, v4
	v_mul_f32_e32 v3, v3, v4
	v_cvt_pk_bf16_f32 v2, v2, v3
	v_mul_f32_e32 v3, 0xbfb8aa3b, v10
	v_mul_f32_e32 v4, 0xbfb8aa3b, v11
	v_exp_f32_e32 v3, v3
	v_exp_f32_e32 v4, v4
	v_add_f32_e32 v3, 1.0, v3
	v_add_f32_e32 v4, 1.0, v4
	v_rcp_f32_e32 v3, v3
	v_rcp_f32_e32 v4, v4
	v_mul_f32_e32 v3, v10, v3
	v_mul_f32_e32 v4, v11, v4
	v_mul_f32_e32 v3, v20, v3
	v_mul_f32_e32 v4, v21, v4
	v_cvt_pk_bf16_f32 v3, v3, v4
	v_mad_i64_i32 v[4:5], s[36:37], v19, s31, v[118:119]
	v_lshl_add_u64 v[4:5], v[4:5], 0, v[120:121]
	global_store_dwordx4 v[4:5], v[0:3], off
	s_cbranch_vccnz .LBB0_283
	s_andn2_b64 vcc, exec, s[0:1]
	s_cbranch_vccnz .LBB0_282
	s_barrier
	s_branch .LBB0_282
